# bisection partial counts in two tiers: first key group when >=2048 survivors known, first two groups when >=1024
# baseline (speedup 1.0000x reference)
; #define PAIR_XCHG(SLOT, TAG, MINE, OTHER) do { const unsigned tg_ = (seq << 8) | (unsigned)(TAG); if (lane == 0) xw[w * 4 + (SLOT)] = ((MINE) << 16) | tg_; \
;             unsigned v_; do { v_ = xw[(w ^ 1) * 4 + (SLOT)]; } while ((v_ & 0xffffu) != tg_); OTHER = v_ >> 16; } while (0)
; __device__ __forceinline__ void attn_item(const Ptrs& P, unsigned char* lds, int b, int tq0, int tid) {
;     ...
;             const unsigned cand = th | (1u << bit); unsigned cnt = 0, oth;
; #pragma unroll
;             for (int k = 0; k < 4; ++k) if (16 * k < nact) {
; #pragma unroll
;                 for (int r = 16 * k; r < 16 * k + 16; ++r) cnt += (unsigned)__popcll(__ballot(k2[r] >= cand)); }
;             PAIR_XCHG(bit & 1, 1 + bit, cnt, oth);
;             cnt += oth;
;             if (cnt >= 256u) th = cand;
;             if (cnt == 256u) break;
.Lbis_loop:
	s_lshl_b32 s12, 1, s75
	s_or_b32 s12, s85, s12
	s_lshr_b32 s13, s12, 16
	s_cmp_gt_u32 s13, s84
	s_cbranch_scc1 .Lbis_next
	v_mov_b32_e32 v24, s12
	v_mov_b32_e32 v25, 0
	v_add_u32_e32 v26, -1, v24
	s_mov_b32 s90, 0
	s_cmp_lt_u32 s97, 0x400
	s_cbranch_scc1 .Lbis_full
	s_cmp_lt_u32 s93, 64
	s_cbranch_scc1 .Lbis_full
	s_cmp_lt_u32 s97, 0x800
	s_cbranch_scc1 .Lbis_pB
	v_med3_u32 v38, v6, v26, v24
	v_med3_u32 v39, v95, v26, v24
	v_add3_u32 v25, v25, v38, v39
	v_med3_u32 v40, v94, v26, v24
	v_med3_u32 v41, v93, v26, v24
	v_add3_u32 v25, v25, v40, v41
	v_med3_u32 v42, v92, v26, v24
	v_med3_u32 v43, v91, v26, v24
	v_add3_u32 v25, v25, v42, v43
	v_med3_u32 v44, v90, v26, v24
	v_med3_u32 v45, v89, v26, v24
	v_add3_u32 v25, v25, v44, v45
	v_med3_u32 v38, v88, v26, v24
	v_med3_u32 v39, v87, v26, v24
	v_add3_u32 v25, v25, v38, v39
	v_med3_u32 v40, v86, v26, v24
	v_med3_u32 v41, v85, v26, v24
	v_add3_u32 v25, v25, v40, v41
	v_med3_u32 v42, v84, v26, v24
	v_med3_u32 v43, v83, v26, v24
	v_add3_u32 v25, v25, v42, v43
	v_med3_u32 v44, v82, v26, v24
	v_med3_u32 v45, v81, v26, v24
	v_add3_u32 v25, v25, v44, v45
	s_mov_b32 s90, 16
	s_sub_u32 s91, s12, 1
	s_mul_i32 s91, s91, s90
	v_subrev_u32_e32 v25, s91, v25
	s_add_i32 s13, s75, 1
	s_or_b32 s13, s86, s13
	v_add_u32_dpp v25, v25, v25 row_ror:1 row_mask:0xf bank_mask:0xf
	s_nop 1
	v_add_u32_dpp v25, v25, v25 row_ror:2 row_mask:0xf bank_mask:0xf
	s_nop 1
	v_add_u32_dpp v25, v25, v25 row_ror:4 row_mask:0xf bank_mask:0xf
	s_nop 1
	v_add_u32_dpp v25, v25, v25 row_ror:8 row_mask:0xf bank_mask:0xf
	v_mov_b32_e32 v36, s87
	v_mov_b32_e32 v37, s88
	v_readlane_b32 s78, v25, 0
	v_readlane_b32 s79, v25, 16
	v_readlane_b32 s90, v25, 32
	v_readlane_b32 s91, v25, 48
	s_mov_b64 s[44:45], exec
	s_nop 2
	s_add_i32 s78, s78, s79
	s_add_i32 s90, s90, s91
	s_add_i32 s78, s78, s90
	s_lshl_b32 s20, s78, 16
	s_or_b32 s20, s20, s13
	v_mov_b32_e32 v27, s20
	s_mov_b64 exec, s[4:5]
	ds_write_b32 v36, v27
	s_mov_b64 exec, s[44:45]

; #define PAIR_XCHG(SLOT, TAG, MINE, OTHER) do { const unsigned tg_ = (seq << 8) | (unsigned)(TAG); if (lane == 0) xw[w * 4 + (SLOT)] = ((MINE) << 16) | tg_; \
;             unsigned v_; do { v_ = xw[(w ^ 1) * 4 + (SLOT)]; } while ((v_ & 0xffffu) != tg_); OTHER = v_ >> 16; } while (0)
; __device__ __forceinline__ void attn_item(const Ptrs& P, unsigned char* lds, int b, int tq0, int tid) {
;     ...
;             const unsigned cand = th | (1u << bit); unsigned cnt = 0, oth;
; #pragma unroll
;             for (int k = 0; k < 4; ++k) if (16 * k < nact) {
; #pragma unroll
;                 for (int r = 16 * k; r < 16 * k + 16; ++r) cnt += (unsigned)__popcll(__ballot(k2[r] >= cand)); }
;             PAIR_XCHG(bit & 1, 1 + bit, cnt, oth);
;             cnt += oth;
;             if (cnt >= 256u) th = cand;
;             if (cnt == 256u) break;
.Lbis_pB:
	v_med3_u32 v38, v6, v26, v24
	v_med3_u32 v39, v95, v26, v24
	v_add3_u32 v25, v25, v38, v39
	v_med3_u32 v40, v94, v26, v24
	v_med3_u32 v41, v93, v26, v24
	v_add3_u32 v25, v25, v40, v41
	v_med3_u32 v42, v92, v26, v24
	v_med3_u32 v43, v91, v26, v24
	v_add3_u32 v25, v25, v42, v43
	v_med3_u32 v44, v90, v26, v24
	v_med3_u32 v45, v89, v26, v24
	v_add3_u32 v25, v25, v44, v45
	v_med3_u32 v38, v88, v26, v24
	v_med3_u32 v39, v87, v26, v24
	v_add3_u32 v25, v25, v38, v39
	v_med3_u32 v40, v86, v26, v24
	v_med3_u32 v41, v85, v26, v24
	v_add3_u32 v25, v25, v40, v41
	v_med3_u32 v42, v84, v26, v24
	v_med3_u32 v43, v83, v26, v24
	v_add3_u32 v25, v25, v42, v43
	v_med3_u32 v44, v82, v26, v24
	v_med3_u32 v45, v81, v26, v24
	v_add3_u32 v25, v25, v44, v45
	v_med3_u32 v38, v4, v26, v24
	v_med3_u32 v39, v80, v26, v24
	v_add3_u32 v25, v25, v38, v39
	v_med3_u32 v40, v79, v26, v24
	v_med3_u32 v41, v78, v26, v24
	v_add3_u32 v25, v25, v40, v41
	v_med3_u32 v42, v77, v26, v24
	v_med3_u32 v43, v76, v26, v24
	v_add3_u32 v25, v25, v42, v43
	v_med3_u32 v44, v75, v26, v24
	v_med3_u32 v45, v74, v26, v24
	v_add3_u32 v25, v25, v44, v45
	v_med3_u32 v38, v73, v26, v24
	v_med3_u32 v39, v72, v26, v24
	v_add3_u32 v25, v25, v38, v39
	v_med3_u32 v40, v71, v26, v24
	v_med3_u32 v41, v70, v26, v24
	v_add3_u32 v25, v25, v40, v41
	v_med3_u32 v42, v69, v26, v24
	v_med3_u32 v43, v68, v26, v24
	v_add3_u32 v25, v25, v42, v43
	v_med3_u32 v44, v67, v26, v24
	v_med3_u32 v45, v66, v26, v24
	v_add3_u32 v25, v25, v44, v45
	s_mov_b32 s90, 32
	s_sub_u32 s91, s12, 1
	s_mul_i32 s91, s91, s90
	v_subrev_u32_e32 v25, s91, v25
	s_add_i32 s13, s75, 1
	s_or_b32 s13, s86, s13
	v_add_u32_dpp v25, v25, v25 row_ror:1 row_mask:0xf bank_mask:0xf
	s_nop 1
	v_add_u32_dpp v25, v25, v25 row_ror:2 row_mask:0xf bank_mask:0xf
	s_nop 1
	v_add_u32_dpp v25, v25, v25 row_ror:4 row_mask:0xf bank_mask:0xf
	s_nop 1
	v_add_u32_dpp v25, v25, v25 row_ror:8 row_mask:0xf bank_mask:0xf
	v_mov_b32_e32 v36, s87
	v_mov_b32_e32 v37, s88
	v_readlane_b32 s78, v25, 0
	v_readlane_b32 s79, v25, 16
	v_readlane_b32 s90, v25, 32
	v_readlane_b32 s91, v25, 48
	s_mov_b64 s[44:45], exec
	s_nop 2
	s_add_i32 s78, s78, s79
	s_add_i32 s90, s90, s91
	s_add_i32 s78, s78, s90
	s_lshl_b32 s20, s78, 16
	s_or_b32 s20, s20, s13
	v_mov_b32_e32 v27, s20
	s_mov_b64 exec, s[4:5]
	ds_write_b32 v36, v27
	s_mov_b64 exec, s[44:45]
.Lbis_spinQ:
	ds_read_b32 v27, v37
	s_waitcnt lgkmcnt(0)
	v_readfirstlane_b32 s20, v27
	s_nop 3
	s_and_b32 s89, s20, 0xffff
	s_cmp_eq_u32 s89, s13
	s_cbranch_scc0 .Lbis_spinQ
	s_lshr_b32 s20, s20, 16
	s_xor_b32 s87, s87, 4
	s_xor_b32 s88, s88, 4
	s_mov_b32 s92, s78
	s_add_i32 s78, s78, s20
	s_cmp_gt_u32 s78, 0xff
	s_cbranch_scc0 .Lbis_r2B
	s_mov_b32 s85, s12
	s_mov_b32 s96, 0
	s_lshl_b32 s97, s78, 1
	s_branch .Lbis_next
.Lbis_r2B:
	v_mov_b32_e32 v25, 0
	s_mov_b32 s90, 0
	s_cmp_eq_u64 s[14:15], 0
	s_cbranch_scc1 .Lbis_cntS
	v_med3_u32 v38, v2, v26, v24
	v_med3_u32 v39, v65, v26, v24
	v_add3_u32 v25, v25, v38, v39
	v_med3_u32 v40, v64, v26, v24
	v_med3_u32 v41, v49, v26, v24
	v_add3_u32 v25, v25, v40, v41
	v_med3_u32 v42, v48, v26, v24
	v_med3_u32 v43, v46, v26, v24
	v_add3_u32 v25, v25, v42, v43
	v_med3_u32 v44, v35, v26, v24
	v_med3_u32 v45, v34, v26, v24
	v_add3_u32 v25, v25, v44, v45
	v_med3_u32 v38, v33, v26, v24
	v_med3_u32 v39, v32, v26, v24
	v_add3_u32 v25, v25, v38, v39
	v_med3_u32 v40, v31, v26, v24
	v_med3_u32 v41, v30, v26, v24
	v_add3_u32 v25, v25, v40, v41
	v_med3_u32 v42, v28, v26, v24
	v_med3_u32 v43, v23, v26, v24
	v_add3_u32 v25, v25, v42, v43
	v_med3_u32 v44, v22, v26, v24
	v_med3_u32 v45, v21, v26, v24
	v_add3_u32 v25, v25, v44, v45
	s_mov_b32 s90, 16
	s_cmp_eq_u64 vcc, 0
	s_cbranch_scc1 .Lbis_cntS
	v_med3_u32 v38, v0, v26, v24
	v_med3_u32 v39, v20, v26, v24
	v_add3_u32 v25, v25, v38, v39
	v_med3_u32 v40, v19, v26, v24
	v_med3_u32 v41, v18, v26, v24
	v_add3_u32 v25, v25, v40, v41
	v_med3_u32 v42, v17, v26, v24
	v_med3_u32 v43, v16, v26, v24
	v_add3_u32 v25, v25, v42, v43
	v_med3_u32 v44, v15, v26, v24
	v_med3_u32 v45, v14, v26, v24
	v_add3_u32 v25, v25, v44, v45
	v_med3_u32 v38, v13, v26, v24
	v_med3_u32 v39, v12, v26, v24
	v_add3_u32 v25, v25, v38, v39
	v_med3_u32 v40, v11, v26, v24
	v_med3_u32 v41, v10, v26, v24
	v_add3_u32 v25, v25, v40, v41
	v_med3_u32 v42, v9, v26, v24
	v_med3_u32 v43, v8, v26, v24
	v_add3_u32 v25, v25, v42, v43
	v_med3_u32 v44, v7, v26, v24
	v_med3_u32 v45, v3, v26, v24
	v_add3_u32 v25, v25, v44, v45
	s_mov_b32 s90, 32

.Lbis_next:
	s_cmp_eq_u32 s75, 0
	s_cbranch_scc1 .Lbis_done
	s_sub_i32 s75, s75, 1
	s_branch .Lbis_loop
	s_nop 0
	s_nop 0
	s_nop 0
	s_nop 0
	s_nop 0
	s_nop 0
	s_nop 0
	s_nop 0
	s_nop 0
